# S5: projection MFMAs batched, 4-FMA scan step in both passes
# baseline (speedup 1.0000x reference)
.LBB0_992:
	s_or_b64 exec, exec, s[14:15]
	v_mfma_f32_16x16x32_bf16 v[94:97], v[80:83], v[4:7], 0
	v_add_u32_e32 v1, 0x400, v157
	v_mul_f32_e32 v2, v140, v92
	v_fmac_f32_e32 v2, v138, v93
	v_mfma_f32_16x16x32_bf16 v[98:101], v[80:83], v[8:11], 0
	s_nop 7
	ds_write2_b32 v157, v94, v98 offset1:16
	ds_write2_b32 v157, v95, v99 offset0:132 offset1:148
	v_mfma_f32_16x16x32_bf16 v[106:109], v[80:83], v[16:19], 0
	ds_write2_b32 v1, v96, v100 offset0:8 offset1:24
	ds_write2_b32 v1, v97, v101 offset0:140 offset1:156
	s_nop 5
	ds_write2_b32 v158, v106, v107 offset1:132
	v_add_u32_e32 v94, 0x400, v158
	v_mfma_f32_16x16x32_bf16 v[102:105], v[80:83], v[12:15], 0
	v_add_u32_e32 v95, 0x400, v159
	v_lshl_add_u64 v[90:91], v[90:91], 0, s[12:13]
	s_cmpk_lt_u32 s16, 0x1f0
	v_mfma_f32_16x16x32_bf16 v[96:99], v[80:83], v[20:23], 0
	ds_write2_b32 v94, v108, v109 offset0:8 offset1:140
	s_nop 6
	ds_write2_b32 v157, v102, v96 offset0:32 offset1:64
	v_mfma_f32_16x16x32_bf16 v[106:109], v[80:83], v[24:27], 0
	ds_write2_b32 v157, v103, v97 offset0:164 offset1:196
	ds_write2_b32 v1, v104, v98 offset0:40 offset1:72
	ds_write2_b32 v1, v105, v99 offset0:172 offset1:204
	v_mfma_f32_16x16x32_bf16 v[96:99], v[80:83], v[28:31], 0
	s_nop 7
	ds_write2_b32 v157, v106, v96 offset0:80 offset1:96
	ds_write2_b32 v157, v107, v97 offset0:212 offset1:228
	ds_write2_b32 v1, v108, v98 offset0:88 offset1:104
	ds_write2_b32 v1, v109, v99 offset0:220 offset1:236
	v_mfma_f32_16x16x32_bf16 v[80:83], v[80:83], v[32:35], 0
	v_mul_f32_e32 v1, v140, v93
	v_fma_f32 v1, v138, v92, -v1
	v_add_u32_e32 v96, 0x800, v173
	v_add_u32_e32 v97, 0x1000, v173
	v_add_u32_e32 v98, 0x1800, v173
	s_nop 2
	ds_write2_b32 v159, v80, v81 offset1:132
	ds_write2_b32 v95, v82, v83 offset0:8 offset1:140
	s_waitcnt lgkmcnt(0)
	ds_read2_b64 v[80:83], v173 offset1:66
	ds_read2_b64 v[100:103], v173 offset0:132 offset1:198
	ds_read2_b64 v[104:107], v96 offset0:8 offset1:74
	ds_read2_b64 v[108:111], v96 offset0:140 offset1:206
	ds_read2_b64 v[112:115], v97 offset0:16 offset1:82
	ds_read2_b64 v[176:179], v97 offset0:148 offset1:214
	ds_read2_b64 v[180:183], v98 offset0:24 offset1:90
	ds_read2_b64 v[184:187], v98 offset0:156 offset1:222
	s_waitcnt lgkmcnt(7)
	v_fma_f32 v248, v138, v92, v80
	v_fma_f32 v249, v138, v93, v81
	v_fma_f32 v2, -v140, v93, v248
	v_fma_f32 v3, v140, v92, v249
	v_fma_f32 v248, v138, v2, v82
	v_fma_f32 v249, v138, v3, v83
	v_fma_f32 v92, -v140, v3, v248
	v_fma_f32 v93, v140, v2, v249
	s_waitcnt lgkmcnt(6)
	v_fma_f32 v248, v138, v92, v100
	v_fma_f32 v249, v138, v93, v101
	v_fma_f32 v2, -v140, v93, v248
	v_fma_f32 v3, v140, v92, v249
	v_fma_f32 v248, v138, v2, v102
	v_fma_f32 v249, v138, v3, v103
	v_fma_f32 v92, -v140, v3, v248
	v_fma_f32 v93, v140, v2, v249
	s_waitcnt lgkmcnt(5)
	v_fma_f32 v248, v138, v92, v104
	v_fma_f32 v249, v138, v93, v105
	v_fma_f32 v2, -v140, v93, v248
	v_fma_f32 v3, v140, v92, v249
	v_fma_f32 v248, v138, v2, v106
	v_fma_f32 v249, v138, v3, v107
	v_fma_f32 v92, -v140, v3, v248
	v_fma_f32 v93, v140, v2, v249
	s_waitcnt lgkmcnt(4)
	v_fma_f32 v248, v138, v92, v108
	v_fma_f32 v249, v138, v93, v109
	v_fma_f32 v2, -v140, v93, v248
	v_fma_f32 v3, v140, v92, v249
	v_fma_f32 v248, v138, v2, v110
	v_fma_f32 v249, v138, v3, v111
	v_fma_f32 v92, -v140, v3, v248
	v_fma_f32 v93, v140, v2, v249
	s_waitcnt lgkmcnt(3)
	v_fma_f32 v248, v138, v92, v112
	v_fma_f32 v249, v138, v93, v113
	v_fma_f32 v2, -v140, v93, v248
	v_fma_f32 v3, v140, v92, v249
	v_fma_f32 v248, v138, v2, v114
	v_fma_f32 v249, v138, v3, v115
	v_fma_f32 v92, -v140, v3, v248
	v_fma_f32 v93, v140, v2, v249
	s_waitcnt lgkmcnt(2)
	v_fma_f32 v248, v138, v92, v176
	v_fma_f32 v249, v138, v93, v177
	v_fma_f32 v2, -v140, v93, v248
	v_fma_f32 v3, v140, v92, v249
	v_fma_f32 v248, v138, v2, v178
	v_fma_f32 v249, v138, v3, v179
	v_fma_f32 v92, -v140, v3, v248
	v_fma_f32 v93, v140, v2, v249
	s_waitcnt lgkmcnt(1)
	v_fma_f32 v248, v138, v92, v180
	v_fma_f32 v249, v138, v93, v181
	v_fma_f32 v2, -v140, v93, v248
	v_fma_f32 v3, v140, v92, v249
	v_fma_f32 v248, v138, v2, v182
	v_fma_f32 v249, v138, v3, v183
	v_fma_f32 v92, -v140, v3, v248
	v_fma_f32 v93, v140, v2, v249
	s_waitcnt lgkmcnt(0)
	v_fma_f32 v248, v138, v92, v184
	v_fma_f32 v249, v138, v93, v185
	v_fma_f32 v2, -v140, v93, v248
	v_fma_f32 v3, v140, v92, v249
	v_fma_f32 v248, v138, v2, v186
	v_fma_f32 v249, v138, v3, v187
	v_fma_f32 v92, -v140, v3, v248
	v_fma_f32 v93, v140, v2, v249
	v_mov_b64_e32 v[82:83], v[70:71]
	v_mov_b64_e32 v[80:81], v[68:69]
	v_mov_b64_e32 v[68:69], v[72:73]
	v_mov_b64_e32 v[70:71], v[74:75]
	v_mov_b64_e32 v[72:73], v[76:77]
	v_mov_b64_e32 v[74:75], v[78:79]
	s_waitcnt vmcnt(0)
	v_mov_b64_e32 v[76:77], v[84:85]
	v_mov_b64_e32 v[78:79], v[86:87]
	s_cbranch_scc0 .LBB0_995

.LBB0_1010:
	s_or_b64 exec, exec, s[14:15]
	v_mfma_f32_16x16x32_bf16 v[212:215], v[80:83], v[4:7], 0
	v_mfma_f32_16x16x32_bf16 v[216:219], v[80:83], v[8:11], 0
	v_mfma_f32_16x16x32_bf16 v[220:223], v[80:83], v[12:15], 0
	v_mfma_f32_16x16x32_bf16 v[224:227], v[80:83], v[16:19], 0
	v_mfma_f32_16x16x32_bf16 v[232:235], v[80:83], v[20:23], 0
	v_mfma_f32_16x16x32_bf16 v[236:239], v[80:83], v[24:27], 0
	v_mfma_f32_16x16x32_bf16 v[240:243], v[80:83], v[28:31], 0
	v_mfma_f32_16x16x32_bf16 v[244:247], v[80:83], v[32:35], 0
	s_nop 1
	ds_write_b32 v157, v212
	ds_write_b32 v162, v213
	ds_write_b32 v157, v214 offset:1056
	ds_write_b32 v157, v215 offset:1584
	ds_write_b32 v157, v216 offset:64
	ds_write_b32 v162, v217 offset:64
	ds_write_b32 v157, v218 offset:1120
	ds_write_b32 v157, v219 offset:1648
	ds_write_b32 v157, v220 offset:128
	ds_write_b32 v162, v221 offset:128
	ds_write_b32 v157, v222 offset:1184
	ds_write_b32 v157, v223 offset:1712
	ds_write_b32 v158, v224
	ds_write_b32 v163, v225
	ds_write2_b32 v94, v226, v227 offset0:8 offset1:140
	ds_write_b32 v157, v232 offset:256
	ds_write_b32 v162, v233 offset:256
	ds_write_b32 v157, v234 offset:1312
	ds_write_b32 v157, v235 offset:1840
	ds_write_b32 v157, v236 offset:320
	ds_write_b32 v162, v237 offset:320
	ds_write_b32 v157, v238 offset:1376
	ds_write_b32 v157, v239 offset:1904
	ds_write_b32 v157, v240 offset:384
	ds_write_b32 v162, v241 offset:384
	ds_write_b32 v157, v242 offset:1440
	ds_write_b32 v157, v243 offset:1968
	ds_write_b32 v159, v244
	ds_write_b32 v164, v245
	ds_write2_b32 v95, v246, v247 offset0:8 offset1:140
	s_and_saveexec_b64 s[14:15], s[4:5]
	ds_write_b128 v160, v[80:83] offset:12800
	s_or_b64 exec, exec, s[14:15]
	s_cmp_eq_u32 s16, 0
	s_cbranch_scc1 .Ls5_first
	ds_read_b128 v[188:191], v161 offset:8448
	ds_read_b128 v[192:195], v161 offset:8512
	ds_read_b128 v[196:199], v161 offset:8576
	ds_read_b128 v[208:211], v161 offset:8640
	ds_read2_b64 v[80:83], v173 offset1:66
	ds_read2_b64 v[90:93], v173 offset0:132 offset1:198
	ds_read2_b64 v[100:103], v96 offset0:8 offset1:74
	ds_read2_b64 v[104:107], v96 offset0:140 offset1:206
	ds_read2_b64 v[108:111], v97 offset0:16 offset1:82
	ds_read2_b64 v[112:115], v97 offset0:148 offset1:214
	ds_read2_b64 v[174:177], v98 offset0:24 offset1:90
	ds_read2_b64 v[178:181], v98 offset0:156 offset1:222
	s_waitcnt lgkmcnt(11)
	v_mfma_f32_16x16x32_bf16 v[188:191], v[188:191], v[60:63], 0
	s_waitcnt lgkmcnt(10)
	v_mfma_f32_16x16x32_bf16 v[188:191], v[192:195], v[52:55], v[188:191]
	s_waitcnt lgkmcnt(9)
	v_mfma_f32_16x16x32_bf16 v[188:191], v[196:199], v[44:47], v[188:191]
	s_waitcnt lgkmcnt(8)
	v_mfma_f32_16x16x32_bf16 v[188:191], v[208:211], v[36:39], v[188:191]
	v_lshlrev_b32_e32 v200, 16, v200
	v_lshlrev_b32_e32 v202, 16, v202
	s_nop 7
	v_fma_f32 v200, v135, v200, v188
	v_mul_f32_e32 v203, 0x3d372713, v200
	v_mul_f32_e32 v203, v200, v203
	v_fma_f32 v203, v200, v203, v200
	v_mul_f32_e32 v203, 0xbfcc422a, v203
	v_mul_f32_e32 v203, 0x3fb8aa3b, v203
	v_exp_f32_e32 v203, v203
	s_nop 0
	v_add_f32_e32 v203, 1.0, v203
	v_div_scale_f32 v205, s[14:15], v203, v203, v200
	v_rcp_f32_e32 v188, v205
	s_nop 0
	v_fma_f32 v206, -v205, v188, 1.0
	v_fmac_f32_e32 v188, v206, v188
	v_div_scale_f32 v206, vcc, v200, v203, v200
	v_mul_f32_e32 v207, v206, v188
	v_fma_f32 v192, -v205, v207, v206
	v_fmac_f32_e32 v207, v192, v188
	v_fma_f32 v205, -v205, v207, v206
	v_div_fmas_f32 v205, v205, v188, v207
	v_div_fixup_f32 v200, v205, v203, v200
	v_fma_f32 v205, v135, v202, v189
	v_mul_f32_e32 v202, 0x3d372713, v205
	v_mul_f32_e32 v202, v205, v202
	v_fma_f32 v202, v205, v202, v205
	v_mul_f32_e32 v202, 0xbfcc422a, v202
	v_mul_f32_e32 v202, 0x3fb8aa3b, v202
	v_exp_f32_e32 v188, v202
	v_add_u32_e32 v189, s17, v64
	v_add_u32_e32 v202, 0, v189
	v_ashrrev_i32_e32 v203, 31, v202
	v_add_f32_e32 v188, 1.0, v188
	v_div_scale_f32 v206, s[14:15], v188, v188, v205
	v_rcp_f32_e32 v207, v206
	v_lshlrev_b64 v[202:203], 11, v[202:203]
	v_cvt_pk_bf16_f32 v200, v200, s0
	v_lshl_add_u64 v[202:203], v[48:49], 0, v[202:203]
	global_store_short v[202:203], v200, off
	v_fma_f32 v200, -v206, v207, 1.0
	v_fmac_f32_e32 v207, v200, v207
	v_div_scale_f32 v200, vcc, v205, v188, v205
	v_mul_f32_e32 v202, v200, v207
	v_fma_f32 v203, -v206, v202, v200
	v_fmac_f32_e32 v202, v203, v207
	v_fma_f32 v200, -v206, v202, v200
	v_div_fmas_f32 v200, v200, v207, v202
	v_lshlrev_b32_e32 v202, 16, v201
	v_fma_f32 v201, v135, v202, v190
	v_mul_f32_e32 v202, 0x3d372713, v201
	v_mul_f32_e32 v202, v201, v202
	v_fma_f32 v202, v201, v202, v201
	v_mul_f32_e32 v202, 0xbfcc422a, v202
	v_mul_f32_e32 v202, 0x3fb8aa3b, v202
	v_div_fixup_f32 v200, v200, v188, v205
	v_exp_f32_e32 v205, v202
	v_add_u32_e32 v202, 1, v189
	v_ashrrev_i32_e32 v203, 31, v202
	v_lshlrev_b64 v[202:203], 11, v[202:203]
	v_add_f32_e32 v205, 1.0, v205
	v_div_scale_f32 v188, s[14:15], v205, v205, v201
	v_rcp_f32_e32 v190, v188
	v_cvt_pk_bf16_f32 v200, v200, s0
	v_lshl_add_u64 v[202:203], v[48:49], 0, v[202:203]
	global_store_short v[202:203], v200, off
	v_fma_f32 v200, -v188, v190, 1.0
	v_fmac_f32_e32 v190, v200, v190
	v_div_scale_f32 v200, vcc, v201, v205, v201
	v_mul_f32_e32 v202, v200, v190
	v_fma_f32 v203, -v188, v202, v200
	v_fmac_f32_e32 v202, v203, v190
	v_fma_f32 v200, -v188, v202, v200
	v_div_fmas_f32 v200, v200, v190, v202
	v_lshlrev_b32_e32 v202, 16, v204
	v_fmac_f32_e32 v191, v135, v202
	v_mul_f32_e32 v202, 0x3d372713, v191
	v_mul_f32_e32 v202, v191, v202
	v_fma_f32 v202, v191, v202, v191
	v_mul_f32_e32 v202, 0xbfcc422a, v202
	v_mul_f32_e32 v202, 0x3fb8aa3b, v202
	v_div_fixup_f32 v200, v200, v205, v201
	v_exp_f32_e32 v201, v202
	v_add_u32_e32 v202, 2, v189
	v_ashrrev_i32_e32 v203, 31, v202
	v_lshlrev_b64 v[202:203], 11, v[202:203]
	v_add_f32_e32 v201, 1.0, v201
	v_div_scale_f32 v204, s[14:15], v201, v201, v191
	v_rcp_f32_e32 v205, v204
	v_cvt_pk_bf16_f32 v200, v200, s0
	v_lshl_add_u64 v[202:203], v[48:49], 0, v[202:203]
	global_store_short v[202:203], v200, off
	v_fma_f32 v200, -v204, v205, 1.0
	v_fmac_f32_e32 v205, v200, v205
	v_div_scale_f32 v200, vcc, v191, v201, v191
	v_mul_f32_e32 v202, v200, v205
	v_fma_f32 v203, -v204, v202, v200
	v_fmac_f32_e32 v202, v203, v205
	v_fma_f32 v200, -v204, v202, v200
	v_div_fmas_f32 v200, v200, v205, v202
	v_add_u32_e32 v202, 3, v189
	v_ashrrev_i32_e32 v203, 31, v202
	v_div_fixup_f32 v200, v200, v201, v191
	v_lshlrev_b64 v[202:203], 11, v[202:203]
	v_cvt_pk_bf16_f32 v200, v200, s0
	v_lshl_add_u64 v[202:203], v[48:49], 0, v[202:203]
	global_store_short v[202:203], v200, off
	s_branch .Ls5_scan

.Ls5_scan:
	s_cmpk_lt_u32 s16, 0x1f0
	v_lshl_add_u64 v[88:89], v[88:89], 0, s[12:13]
	s_waitcnt lgkmcnt(7)
	v_fma_f32 v66, v138, v84, v80
	v_fma_f32 v67, v138, v85, v81
	v_fma_f32 v2, -v140, v85, v66
	v_fma_f32 v3, v140, v84, v67
	v_cvt_pk_bf16_f32 v1, v2, v3
	ds_write_b32 v165, v1 offset:8448
	v_fma_f32 v66, v138, v2, v82
	v_fma_f32 v67, v138, v3, v83
	v_fma_f32 v84, -v140, v3, v66
	v_fma_f32 v85, v140, v2, v67
	v_cvt_pk_bf16_f32 v65, v84, v85
	ds_write_b32 v165, v65 offset:8720
	s_waitcnt lgkmcnt(8)
	v_fma_f32 v66, v138, v84, v90
	v_fma_f32 v67, v138, v85, v91
	v_fma_f32 v2, -v140, v85, v66
	v_fma_f32 v3, v140, v84, v67
	v_cvt_pk_bf16_f32 v1, v2, v3
	ds_write_b32 v165, v1 offset:8992
	v_fma_f32 v66, v138, v2, v92
	v_fma_f32 v67, v138, v3, v93
	v_fma_f32 v84, -v140, v3, v66
	v_fma_f32 v85, v140, v2, v67
	v_cvt_pk_bf16_f32 v65, v84, v85
	ds_write_b32 v165, v65 offset:9264
	s_waitcnt lgkmcnt(9)
	v_fma_f32 v66, v138, v84, v100
	v_fma_f32 v67, v138, v85, v101
	v_fma_f32 v2, -v140, v85, v66
	v_fma_f32 v3, v140, v84, v67
	v_cvt_pk_bf16_f32 v1, v2, v3
	ds_write_b32 v165, v1 offset:9536
	v_fma_f32 v66, v138, v2, v102
	v_fma_f32 v67, v138, v3, v103
	v_fma_f32 v84, -v140, v3, v66
	v_fma_f32 v85, v140, v2, v67
	v_cvt_pk_bf16_f32 v65, v84, v85
	ds_write_b32 v165, v65 offset:9808
	s_waitcnt lgkmcnt(10)
	v_fma_f32 v66, v138, v84, v104
	v_fma_f32 v67, v138, v85, v105
	v_fma_f32 v2, -v140, v85, v66
	v_fma_f32 v3, v140, v84, v67
	v_cvt_pk_bf16_f32 v1, v2, v3
	ds_write_b32 v165, v1 offset:10080
	v_fma_f32 v66, v138, v2, v106
	v_fma_f32 v67, v138, v3, v107
	v_fma_f32 v84, -v140, v3, v66
	v_fma_f32 v85, v140, v2, v67
	v_cvt_pk_bf16_f32 v65, v84, v85
	ds_write_b32 v165, v65 offset:10352
	s_waitcnt lgkmcnt(11)
	v_fma_f32 v66, v138, v84, v108
	v_fma_f32 v67, v138, v85, v109
	v_fma_f32 v2, -v140, v85, v66
	v_fma_f32 v3, v140, v84, v67
	v_cvt_pk_bf16_f32 v1, v2, v3
	ds_write_b32 v165, v1 offset:10624
	v_fma_f32 v66, v138, v2, v110
	v_fma_f32 v67, v138, v3, v111
	v_fma_f32 v84, -v140, v3, v66
	v_fma_f32 v85, v140, v2, v67
	v_cvt_pk_bf16_f32 v65, v84, v85
	ds_write_b32 v165, v65 offset:10896
	s_waitcnt lgkmcnt(12)
	v_fma_f32 v66, v138, v84, v112
	v_fma_f32 v67, v138, v85, v113
	v_fma_f32 v2, -v140, v85, v66
	v_fma_f32 v3, v140, v84, v67
	v_cvt_pk_bf16_f32 v1, v2, v3
	ds_write_b32 v165, v1 offset:11168
	v_fma_f32 v66, v138, v2, v114
	v_fma_f32 v67, v138, v3, v115
	v_fma_f32 v84, -v140, v3, v66
	v_fma_f32 v85, v140, v2, v67
	v_cvt_pk_bf16_f32 v65, v84, v85
	ds_write_b32 v165, v65 offset:11440
	s_waitcnt lgkmcnt(13)
	v_fma_f32 v66, v138, v84, v174
	v_fma_f32 v67, v138, v85, v175
	v_fma_f32 v2, -v140, v85, v66
	v_fma_f32 v3, v140, v84, v67
	v_cvt_pk_bf16_f32 v1, v2, v3
	ds_write_b32 v165, v1 offset:11712
	v_fma_f32 v66, v138, v2, v176
	v_fma_f32 v67, v138, v3, v177
	v_fma_f32 v84, -v140, v3, v66
	v_fma_f32 v85, v140, v2, v67
	v_cvt_pk_bf16_f32 v65, v84, v85
	ds_write_b32 v165, v65 offset:11984
	s_waitcnt lgkmcnt(14)
	v_fma_f32 v66, v138, v84, v178
	v_fma_f32 v67, v138, v85, v179
	v_fma_f32 v2, -v140, v85, v66
	v_fma_f32 v3, v140, v84, v67
	v_cvt_pk_bf16_f32 v1, v2, v3
	ds_write_b32 v165, v1 offset:12256
	v_fma_f32 v66, v138, v2, v180
	v_fma_f32 v67, v138, v3, v181
	v_fma_f32 v84, -v140, v3, v66
	v_fma_f32 v85, v140, v2, v67
	v_cvt_pk_bf16_f32 v65, v84, v85
	ds_write_b32 v165, v65 offset:12528
	ds_read_u16 v200, v166 offset:12800
	ds_read_u16 v202, v167 offset:12800
	ds_read_u16 v201, v168 offset:12800
	ds_read_u16 v204, v169 offset:12800
	s_waitcnt lgkmcnt(0)
	s_cbranch_scc0 .Ls5_lastE
	s_waitcnt vmcnt(4)
	v_mov_b64_e32 v[82:83], v[70:71]
	v_mov_b64_e32 v[80:81], v[68:69]
	v_mov_b64_e32 v[68:69], v[72:73]
	v_mov_b64_e32 v[70:71], v[74:75]
	v_mov_b64_e32 v[72:73], v[76:77]
	v_mov_b64_e32 v[74:75], v[78:79]
	v_mov_b64_e32 v[78:79], v[42:43]
	s_mov_b32 s17, s16
	v_mov_b64_e32 v[76:77], v[40:41]
	s_branch .LBB0_1008
